# v142 with the P6-P8, P8-P9, P9-P10 barriers among the 4 workgroups of a row tile instead of the 32-workgroup class
# speedup vs baseline: 1.0034x; 1.0008x over previous
.Llb790_go:
	s_and_b32 s0, s74, 63
	s_lshl_b32 s0, s0, 8
	s_add_u32 s0, s0, 0x6000
	s_add_u32 s2, s92, s0
	s_addc_u32 s3, s93, 0
	v_mov_b32_e32 v0, 1
	s_waitcnt vmcnt(0) lgkmcnt(0)
	s_add_u32 s12, s92, 0x5100
	s_addc_u32 s13, s93, 0
	global_load_dword v2, v197, s[12:13] sc1
	global_atomic_add v1, v197, v0, s[2:3] sc0
	s_waitcnt vmcnt(0)
	v_readfirstlane_b32 s1, v1
	s_lshr_b32 s8, s1, 2
	s_and_b32 s1, s1, 3
	s_cmp_eq_u32 s1, 3
	s_cbranch_scc1 .Llb790_lead
	s_mov_b32 s9, 0

.Llb882_go:
	s_and_b32 s0, s74, 63
	s_lshl_b32 s0, s0, 8
	s_add_u32 s0, s0, 0x6000
	s_add_u32 s2, s92, s0
	s_addc_u32 s3, s93, 0
	v_mov_b32_e32 v0, 1
	s_waitcnt vmcnt(0) lgkmcnt(0)
	global_atomic_add v1, v197, v0, s[2:3] sc0
	s_waitcnt vmcnt(0)
	v_readfirstlane_b32 s1, v1
	s_lshr_b32 s8, s1, 2
	s_and_b32 s1, s1, 3
	s_cmp_eq_u32 s1, 3
	s_cbranch_scc1 .Llb882_lead
	s_mov_b32 s9, 0
